# attention per-item overhead: tile-0 K/V loads and second-half rope cos/sin loads issued together with the Q loads (one memory round trip instead of three); O rows staged through wave-private LDS and s
# baseline (speedup 1.0000x reference)
.LBB0_32:
	v_mov_b32_e32 v64, v209
	s_nop 1
	v_permlane32_swap_b32_e32 v209, v64
	v_add_f32_e32 v64, v209, v64
	v_div_scale_f32 v65, s[0:1], v64, v64, 1.0
	v_rcp_f32_e32 v66, v65
	s_lshl_b32 s70, s42, 8
	s_barrier
	v_fma_f32 v67, -v65, v66, 1.0
	v_fmac_f32_e32 v66, v67, v66
	v_div_scale_f32 v67, vcc, 1.0, v64, 1.0
	v_mul_f32_e32 v68, v67, v66
	v_fma_f32 v69, -v65, v68, v67
	v_fmac_f32_e32 v68, v69, v66
	v_fma_f32 v65, -v65, v68, v67
	v_div_fmas_f32 v65, v65, v66, v68
	v_lshlrev_b64 v[66:67], 11, v[206:207]
	v_div_fixup_f32 v64, v65, v64, 1.0
	v_readfirstlane_b32 s0, v206
	s_lshr_b32 s1, s25, 5
	v_mbcnt_lo_u32_b32 v70, -1, 0
	v_mbcnt_hi_u32_b32 v70, -1, v70
	s_mul_i32 s5, s1, 8704
	s_add_i32 s5, s5, 25600
	s_cmp_ge_u32 s1, 2
	s_cselect_b32 s7, 28672, 0
	s_add_i32 s5, s5, s7
	s_cmp_ge_u32 s1, 6
	s_cselect_b32 s7, 6144, 0
	s_add_i32 s5, s5, s7
	s_movk_i32 s7, 272
	v_and_b32_e32 v65, 31, v70
	v_mul_u32_u24_e32 v65, s7, v65
	v_lshl_add_u32 v65, v188, 1, v65
	v_add_u32_e32 v65, s5, v65
	v_lshrrev_b32_e32 v66, 4, v70
	v_and_b32_e32 v67, 15, v70
	v_mul_u32_u24_e32 v68, s7, v66
	v_lshl_add_u32 v68, v67, 4, v68
	v_add_u32_e32 v68, s5, v68
	v_add_u32_e32 v69, s0, v66
	v_lshlrev_b32_e32 v69, 11, v69
	v_lshl_add_u32 v69, v67, 4, v69
	v_add_u32_e32 v69, s70, v69
	v_pk_mul_f32 v[48:49], v[48:49], v[64:65] op_sel_hi:[1,0]
	v_pk_mul_f32 v[50:51], v[50:51], v[64:65] op_sel_hi:[1,0]
	v_pk_mul_f32 v[52:53], v[52:53], v[64:65] op_sel_hi:[1,0]
	v_pk_mul_f32 v[54:55], v[54:55], v[64:65] op_sel_hi:[1,0]
	v_pk_mul_f32 v[56:57], v[56:57], v[64:65] op_sel_hi:[1,0]
	v_pk_mul_f32 v[58:59], v[58:59], v[64:65] op_sel_hi:[1,0]
	v_pk_mul_f32 v[60:61], v[60:61], v[64:65] op_sel_hi:[1,0]
	v_pk_mul_f32 v[62:63], v[62:63], v[64:65] op_sel_hi:[1,0]
	v_pk_mul_f32 v[32:33], v[32:33], v[64:65] op_sel_hi:[1,0]
	v_pk_mul_f32 v[34:35], v[34:35], v[64:65] op_sel_hi:[1,0]
	v_pk_mul_f32 v[36:37], v[36:37], v[64:65] op_sel_hi:[1,0]
	v_pk_mul_f32 v[38:39], v[38:39], v[64:65] op_sel_hi:[1,0]
	v_pk_mul_f32 v[40:41], v[40:41], v[64:65] op_sel_hi:[1,0]
	v_pk_mul_f32 v[42:43], v[42:43], v[64:65] op_sel_hi:[1,0]
	v_pk_mul_f32 v[44:45], v[44:45], v[64:65] op_sel_hi:[1,0]
	v_pk_mul_f32 v[46:47], v[46:47], v[64:65] op_sel_hi:[1,0]
	v_pk_mul_f32 v[16:17], v[16:17], v[64:65] op_sel_hi:[1,0]
	v_pk_mul_f32 v[18:19], v[18:19], v[64:65] op_sel_hi:[1,0]
	v_pk_mul_f32 v[20:21], v[20:21], v[64:65] op_sel_hi:[1,0]
	v_pk_mul_f32 v[22:23], v[22:23], v[64:65] op_sel_hi:[1,0]
	v_pk_mul_f32 v[24:25], v[24:25], v[64:65] op_sel_hi:[1,0]
	v_pk_mul_f32 v[26:27], v[26:27], v[64:65] op_sel_hi:[1,0]
	v_pk_mul_f32 v[28:29], v[28:29], v[64:65] op_sel_hi:[1,0]
	v_pk_mul_f32 v[30:31], v[30:31], v[64:65] op_sel_hi:[1,0]
	v_pk_mul_f32 v[0:1], v[0:1], v[64:65] op_sel_hi:[1,0]
	v_pk_mul_f32 v[2:3], v[2:3], v[64:65] op_sel_hi:[1,0]
	v_pk_mul_f32 v[4:5], v[4:5], v[64:65] op_sel_hi:[1,0]
	v_pk_mul_f32 v[6:7], v[6:7], v[64:65] op_sel_hi:[1,0]
	v_pk_mul_f32 v[8:9], v[8:9], v[64:65] op_sel_hi:[1,0]
	v_pk_mul_f32 v[10:11], v[10:11], v[64:65] op_sel_hi:[1,0]
	v_pk_mul_f32 v[12:13], v[12:13], v[64:65] op_sel_hi:[1,0]
	v_pk_mul_f32 v[14:15], v[14:15], v[64:65] op_sel_hi:[1,0]
	v_cvt_pk_bf16_f32 v48, v48, v49
	v_cvt_pk_bf16_f32 v49, v50, v51
	v_cvt_pk_bf16_f32 v50, v52, v53
	v_cvt_pk_bf16_f32 v51, v54, v55
	v_cvt_pk_bf16_f32 v52, v56, v57
	v_cvt_pk_bf16_f32 v53, v58, v59
	v_cvt_pk_bf16_f32 v54, v60, v61
	v_cvt_pk_bf16_f32 v55, v62, v63
	v_cvt_pk_bf16_f32 v32, v32, v33
	v_cvt_pk_bf16_f32 v33, v34, v35
	v_cvt_pk_bf16_f32 v34, v36, v37
	v_cvt_pk_bf16_f32 v35, v38, v39
	v_cvt_pk_bf16_f32 v36, v40, v41
	v_cvt_pk_bf16_f32 v37, v42, v43
	v_cvt_pk_bf16_f32 v38, v44, v45
	v_cvt_pk_bf16_f32 v39, v46, v47
	v_cvt_pk_bf16_f32 v16, v16, v17
	v_cvt_pk_bf16_f32 v17, v18, v19
	v_cvt_pk_bf16_f32 v18, v20, v21
	v_cvt_pk_bf16_f32 v19, v22, v23
	v_cvt_pk_bf16_f32 v20, v24, v25
	v_cvt_pk_bf16_f32 v21, v26, v27
	v_cvt_pk_bf16_f32 v22, v28, v29
	v_cvt_pk_bf16_f32 v23, v30, v31
	v_cvt_pk_bf16_f32 v0, v0, v1
	v_cvt_pk_bf16_f32 v1, v2, v3
	v_cvt_pk_bf16_f32 v2, v4, v5
	v_cvt_pk_bf16_f32 v3, v6, v7
	v_cvt_pk_bf16_f32 v4, v8, v9
	v_cvt_pk_bf16_f32 v5, v10, v11
	v_cvt_pk_bf16_f32 v6, v12, v13
	v_cvt_pk_bf16_f32 v7, v14, v15
	ds_write_b64 v65, v[48:49] offset:0
	ds_write_b64 v65, v[50:51] offset:16
	ds_write_b64 v65, v[52:53] offset:32
	ds_write_b64 v65, v[54:55] offset:48
	ds_write_b64 v65, v[32:33] offset:64
	ds_write_b64 v65, v[34:35] offset:80
	ds_write_b64 v65, v[36:37] offset:96
	ds_write_b64 v65, v[38:39] offset:112
	s_waitcnt lgkmcnt(4)
	ds_write_b64 v65, v[16:17] offset:128
	ds_write_b64 v65, v[18:19] offset:144
	ds_write_b64 v65, v[20:21] offset:160
	ds_write_b64 v65, v[22:23] offset:176
	ds_write_b64 v65, v[0:1] offset:192
	ds_write_b64 v65, v[2:3] offset:208
	ds_write_b64 v65, v[4:5] offset:224
	ds_write_b64 v65, v[6:7] offset:240
	s_waitcnt lgkmcnt(0)
	ds_read_b128 v[72:75], v68 offset:0
	ds_read_b128 v[76:79], v68 offset:1088
	ds_read_b128 v[80:83], v68 offset:2176
	ds_read_b128 v[84:87], v68 offset:3264
	ds_read_b128 v[88:91], v68 offset:4352
	ds_read_b128 v[92:95], v68 offset:5440
	ds_read_b128 v[0:3], v68 offset:6528
	ds_read_b128 v[4:7], v68 offset:7616
	s_waitcnt lgkmcnt(7)
	global_store_dwordx4 v69, v[72:75], s[92:93]
	v_add_u32_e32 v69, 0x2000, v69
	s_waitcnt lgkmcnt(6)
	global_store_dwordx4 v69, v[76:79], s[92:93]
	v_add_u32_e32 v69, 0x2000, v69
	s_waitcnt lgkmcnt(5)
	global_store_dwordx4 v69, v[80:83], s[92:93]
	v_add_u32_e32 v69, 0x2000, v69
	s_waitcnt lgkmcnt(4)
	global_store_dwordx4 v69, v[84:87], s[92:93]
	v_add_u32_e32 v69, 0x2000, v69
	s_waitcnt lgkmcnt(3)
	global_store_dwordx4 v69, v[88:91], s[92:93]
	v_add_u32_e32 v69, 0x2000, v69
	s_waitcnt lgkmcnt(2)
	global_store_dwordx4 v69, v[92:95], s[92:93]
	v_add_u32_e32 v69, 0x2000, v69
	s_waitcnt lgkmcnt(1)
	global_store_dwordx4 v69, v[0:3], s[92:93]
	v_add_u32_e32 v69, 0x2000, v69
	s_waitcnt lgkmcnt(0)
	global_store_dwordx4 v69, v[4:7], s[92:93]
	v_readlane_b32 s0, v254, 7
	s_add_i32 s29, s29, s94
	s_add_i32 s28, s28, s0
	s_add_i32 s24, s24, s94
	s_cmpk_gt_i32 s29, 0x3ff
	v_readlane_b32 s1, v254, 8
	s_cbranch_scc1 .LBB0_52

.LBB0_39:
	s_lshl_b32 s0, s28, 7
	s_and_b32 s70, s0, 0x380000
	s_lshl_b32 s0, s28, 12
	s_and_b32 s1, s24, 7
	s_and_b32 s0, s0, 0x7000000
	s_lshl_b32 s1, s1, 9
	v_lshl_add_u64 v[210:211], v[196:197], 0, s[70:71]
	s_or_b32 s70, s1, s0
	s_lshl_b32 s0, s5, 8
	s_add_i32 s43, s0, s25
	s_lshl_b32 s1, s29, 9
	v_or_b32_e32 v208, s43, v189
	v_lshl_add_u64 v[212:213], s[70:71], 0, v[198:199]
	v_lshl_add_u64 v[214:215], s[70:71], 0, v[200:201]
	v_lshl_add_u64 v[216:217], s[70:71], 0, v[202:203]
	v_lshl_add_u64 v[218:219], s[70:71], 0, v[204:205]
	s_and_b32 s70, s1, 0x7000
	v_ashrrev_i32_e32 v209, 31, v208
	v_lshl_add_u64 v[206:207], v[208:209], 0, s[70:71]
	v_mov_b64_e32 v[0:1], s[14:15]
	s_and_b32 s42, s29, 7
	v_mad_u64_u32 v[0:1], s[38:39], v206, s10, v[0:1]
	v_mad_i32_i24 v1, v207, s10, v1
	s_mul_i32 s38, s42, 0x180
	s_mov_b32 s39, s71
	v_lshl_add_u64 v[0:1], v[0:1], 0, s[38:39]
	v_lshlrev_b64 v[20:21], 7, v[206:207]
	v_lshl_add_u64 v[4:5], v[0:1], 0, v[164:165]
	v_lshl_add_u64 v[34:35], v[192:193], 0, v[20:21]
	v_lshl_add_u64 v[20:21], v[194:195], 0, v[20:21]
	global_load_dwordx4 v[132:135], v[4:5], off
	global_load_dwordx4 v[128:131], v[4:5], off offset:32
	global_load_dwordx4 v[124:127], v[4:5], off offset:64
	global_load_dwordx4 v[116:119], v[4:5], off offset:96
	global_load_dwordx4 v[112:115], v[4:5], off offset:128
	global_load_dwordx4 v[104:107], v[4:5], off offset:160
	global_load_dwordx4 v[100:103], v[4:5], off offset:192
	global_load_dwordx4 v[96:99], v[4:5], off offset:224
	global_load_dwordx4 v[8:11], v[4:5], off offset:256
	global_load_dwordx4 v[0:3], v[4:5], off offset:288
	global_load_dwordx4 v[12:15], v[4:5], off offset:320
	s_nop 0
	global_load_dwordx4 v[4:7], v[4:5], off offset:352
	s_nop 0
	global_load_dwordx4 v[16:19], v[34:35], off offset:16
	global_load_dwordx4 v[22:25], v[34:35], off
	global_load_dwordx4 v[26:29], v[20:21], off offset:16
	global_load_dwordx4 v[30:33], v[20:21], off
	global_load_dwordx4 v[64:67], v[34:35], off offset:80
	global_load_dwordx4 v[68:71], v[34:35], off offset:64
	global_load_dwordx4 v[72:75], v[20:21], off offset:80
	global_load_dwordx4 v[76:79], v[20:21], off offset:64
	s_lshl_b32 s1, s70, 12
	s_add_u32 s1, s96, s1
	s_addc_u32 s5, s97, 0
	s_lshl_b32 s7, s42, 9
	s_add_u32 s38, s1, s7
	s_addc_u32 s39, s5, 0
	s_lshl_b32 s70, s70, 7
	v_lshl_add_u64 v[148:149], v[180:181], 1, s[38:39]
	v_lshl_add_u64 v[150:151], v[182:183], 1, s[38:39]
	v_lshl_add_u64 v[152:153], v[190:191], 0, s[70:71]
	global_load_dwordx4 v[80:83], v[148:149], off
	global_load_dwordx4 v[84:87], v[150:151], off
	global_load_dwordx4 v[88:91], v[152:153], off
	global_load_dwordx4 v[92:95], v[148:149], off offset:256
	global_load_dwordx4 v[144:147], v[150:151], off offset:256
	s_or_b32 s44, s43, 31
	s_or_b32 s45, s0, 0xc0
	s_mov_b32 s46, 0
	v_mov_b32_e32 v209, 0
	v_mov_b32_e32 v247, 0xf149f2ca
	s_mov_b32 s13, 0
	s_waitcnt vmcnt(9)
	v_and_b32_e32 v37, 0xffff0000, v8
	v_lshlrev_b32_e32 v36, 16, v8
	s_waitcnt vmcnt(9)
	v_and_b32_e32 v39, 0xffff0000, v12
	v_lshlrev_b32_e32 v38, 16, v12
	v_lshlrev_b32_e32 v8, 16, v13
	s_waitcnt vmcnt(9)
	v_pk_mul_f32 v[40:41], v[30:31], v[36:37]
	v_pk_mul_f32 v[30:31], v[30:31], v[38:39]
	v_pk_fma_f32 v[40:41], v[22:23], v[38:39], v[40:41]
	v_pk_fma_f32 v[22:23], v[22:23], v[36:37], v[30:31] neg_lo:[0,0,1] neg_hi:[0,0,1]
	v_cvt_pk_bf16_f32 v108, v40, v41
	v_cvt_pk_bf16_f32 v120, v22, v23
	v_and_b32_e32 v23, 0xffff0000, v9
	v_lshlrev_b32_e32 v22, 16, v9
	v_and_b32_e32 v9, 0xffff0000, v13
	v_pk_mul_f32 v[12:13], v[32:33], v[22:23]
	s_nop 0
	v_pk_fma_f32 v[12:13], v[24:25], v[8:9], v[12:13]
	v_pk_mul_f32 v[8:9], v[32:33], v[8:9]
	v_cvt_pk_bf16_f32 v109, v12, v13
	v_pk_fma_f32 v[8:9], v[24:25], v[22:23], v[8:9] neg_lo:[0,0,1] neg_hi:[0,0,1]
	v_and_b32_e32 v13, 0xffff0000, v14
	v_cvt_pk_bf16_f32 v121, v8, v9
	v_and_b32_e32 v9, 0xffff0000, v10
	v_lshlrev_b32_e32 v8, 16, v10
	v_lshlrev_b32_e32 v12, 16, v14
	v_pk_mul_f32 v[22:23], v[26:27], v[8:9]
	v_lshlrev_b32_e32 v10, 16, v15
	v_pk_fma_f32 v[22:23], v[16:17], v[12:13], v[22:23]
	v_pk_mul_f32 v[12:13], v[26:27], v[12:13]
	v_cvt_pk_bf16_f32 v110, v22, v23
	v_pk_fma_f32 v[8:9], v[16:17], v[8:9], v[12:13] neg_lo:[0,0,1] neg_hi:[0,0,1]
	v_and_b32_e32 v25, 0xffff0000, v0
	v_cvt_pk_bf16_f32 v122, v8, v9
	v_and_b32_e32 v9, 0xffff0000, v11
	v_lshlrev_b32_e32 v8, 16, v11
	v_and_b32_e32 v11, 0xffff0000, v15
	v_pk_mul_f32 v[12:13], v[28:29], v[8:9]
	v_lshlrev_b32_e32 v24, 16, v0
	v_pk_fma_f32 v[12:13], v[18:19], v[10:11], v[12:13]
	v_pk_mul_f32 v[10:11], v[28:29], v[10:11]
	v_cvt_pk_bf16_f32 v111, v12, v13
	v_pk_fma_f32 v[8:9], v[18:19], v[8:9], v[10:11] neg_lo:[0,0,1] neg_hi:[0,0,1]
	v_and_b32_e32 v27, 0xffff0000, v4
	v_cvt_pk_bf16_f32 v123, v8, v9
	s_nop 0
	v_lshlrev_b32_e32 v26, 16, v4
	v_lshlrev_b32_e32 v0, 16, v5
	s_waitcnt vmcnt(5)
	v_mov_b32_e32 v8, v64
	v_mov_b32_e32 v9, v65
	v_mov_b32_e32 v10, v66
	v_mov_b32_e32 v11, v67
	v_mov_b32_e32 v16, v68
	v_mov_b32_e32 v17, v69
	v_mov_b32_e32 v18, v70
	v_mov_b32_e32 v19, v71
	v_mov_b32_e32 v12, v72
	v_mov_b32_e32 v13, v73
	v_mov_b32_e32 v14, v74
	v_mov_b32_e32 v15, v75
	v_mov_b32_e32 v20, v76
	v_mov_b32_e32 v21, v77
	v_mov_b32_e32 v22, v78
	v_mov_b32_e32 v23, v79
	v_pk_mul_f32 v[28:29], v[20:21], v[24:25]
	v_pk_mul_f32 v[20:21], v[20:21], v[26:27]
	v_pk_fma_f32 v[28:29], v[16:17], v[26:27], v[28:29]
	v_pk_fma_f32 v[16:17], v[16:17], v[24:25], v[20:21] neg_lo:[0,0,1] neg_hi:[0,0,1]
	v_cvt_pk_bf16_f32 v136, v28, v29
	v_cvt_pk_bf16_f32 v140, v16, v17
	v_and_b32_e32 v17, 0xffff0000, v1
	v_lshlrev_b32_e32 v16, 16, v1
	v_and_b32_e32 v1, 0xffff0000, v5
	v_pk_mul_f32 v[4:5], v[22:23], v[16:17]
	s_nop 0
	v_pk_fma_f32 v[4:5], v[18:19], v[0:1], v[4:5]
	v_pk_mul_f32 v[0:1], v[22:23], v[0:1]
	v_cvt_pk_bf16_f32 v137, v4, v5
	v_pk_fma_f32 v[0:1], v[18:19], v[16:17], v[0:1] neg_lo:[0,0,1] neg_hi:[0,0,1]
	v_and_b32_e32 v5, 0xffff0000, v6
	v_cvt_pk_bf16_f32 v141, v0, v1
	v_and_b32_e32 v1, 0xffff0000, v2
	v_lshlrev_b32_e32 v0, 16, v2
	v_lshlrev_b32_e32 v4, 16, v6
	v_pk_mul_f32 v[16:17], v[12:13], v[0:1]
	v_lshlrev_b32_e32 v2, 16, v7
	v_pk_fma_f32 v[16:17], v[8:9], v[4:5], v[16:17]
	v_pk_mul_f32 v[4:5], v[12:13], v[4:5]
	v_cvt_pk_bf16_f32 v138, v16, v17
	v_pk_fma_f32 v[0:1], v[8:9], v[0:1], v[4:5] neg_lo:[0,0,1] neg_hi:[0,0,1]
	v_cvt_pk_bf16_f32 v142, v0, v1
	v_and_b32_e32 v1, 0xffff0000, v3
	v_lshlrev_b32_e32 v0, 16, v3
	v_and_b32_e32 v3, 0xffff0000, v7
	v_pk_mul_f32 v[4:5], v[14:15], v[0:1]
	v_pk_fma_f32 v[4:5], v[10:11], v[2:3], v[4:5]
	v_pk_mul_f32 v[2:3], v[14:15], v[2:3]
	v_cvt_pk_bf16_f32 v139, v4, v5
	v_pk_fma_f32 v[0:1], v[10:11], v[0:1], v[2:3] neg_lo:[0,0,1] neg_hi:[0,0,1]
	s_nop 0
	v_cvt_pk_bf16_f32 v143, v0, v1
	s_waitcnt vmcnt(0)
	ds_write_b128 v244, v[80:83]
	s_waitcnt vmcnt(2)
	ds_write_b128 v244, v[84:87] offset:12800
	s_waitcnt vmcnt(1)
	ds_write_b128 v245, v[88:91] offset:256
	v_mov_b32_e32 v14, v165
	v_mov_b32_e32 v15, v165
	s_waitcnt vmcnt(0)
	s_movk_i32 s0, 320
	s_movk_i32 s1, 1280
	v_lshrrev_b32_e32 v216, 4, v220
	v_mul_u32_u24_e32 v216, s0, v216
	v_and_b32_e32 v248, 15, v220
	v_lshl_add_u32 v216, v248, 4, v216
	v_and_b32_e32 v217, 3, v220
	v_lshlrev_b32_e32 v217, 3, v217
	v_bfe_u32 v248, v220, 2, 2
	v_mad_u32_u24 v217, v248, s0, v217
	v_bfe_u32 v248, v220, 4, 1
	v_lshl_add_u32 v217, v248, 5, v217
	v_bfe_u32 v248, v220, 5, 1
	v_mad_u32_u24 v217, v248, s1, v217
	ds_write_b128 v216, v[92:95] offset:51200
	ds_write_b128 v216, v[144:147] offset:61440
	v_mov_b32_e32 v0, v165
	v_mov_b32_e32 v1, v165
	v_mov_b32_e32 v2, v165
	v_mov_b32_e32 v3, v165
	v_mov_b32_e32 v4, v165
	v_mov_b32_e32 v5, v165
	v_mov_b32_e32 v6, v165
	v_mov_b32_e32 v7, v165
	v_mov_b32_e32 v8, v165
	v_mov_b32_e32 v9, v165
	v_mov_b32_e32 v10, v165
	v_mov_b32_e32 v11, v165
	v_mov_b32_e32 v12, v165
	v_mov_b32_e32 v13, v165
	v_mov_b64_e32 v[30:31], v[14:15]
	v_mov_b64_e32 v[46:47], v[14:15]
	v_mov_b64_e32 v[62:63], v[14:15]
	v_mov_b64_e32 v[28:29], v[12:13]
	v_mov_b64_e32 v[26:27], v[10:11]
	v_mov_b64_e32 v[24:25], v[8:9]
	v_mov_b64_e32 v[22:23], v[6:7]
	v_mov_b64_e32 v[20:21], v[4:5]
	v_mov_b64_e32 v[18:19], v[2:3]
	v_mov_b64_e32 v[16:17], v[0:1]
	v_mov_b64_e32 v[44:45], v[12:13]
	v_mov_b64_e32 v[42:43], v[10:11]
	v_mov_b64_e32 v[40:41], v[8:9]
	v_mov_b64_e32 v[38:39], v[6:7]
	v_mov_b64_e32 v[36:37], v[4:5]
	v_mov_b64_e32 v[34:35], v[2:3]
	v_mov_b64_e32 v[32:33], v[0:1]
	v_mov_b64_e32 v[60:61], v[12:13]
	v_mov_b64_e32 v[58:59], v[10:11]
	v_mov_b64_e32 v[56:57], v[8:9]
	v_mov_b64_e32 v[54:55], v[6:7]
	v_mov_b64_e32 v[52:53], v[4:5]
	v_mov_b64_e32 v[50:51], v[2:3]
	v_mov_b64_e32 v[48:49], v[0:1]
	s_waitcnt lgkmcnt(0)
	s_barrier
	v_lshl_add_u64 v[248:249], s[20:21], 0, v[212:213]
	global_load_dwordx4 v[152:155], v[248:249], off
	v_lshl_add_u64 v[170:171], s[20:21], 0, v[214:215]
	global_load_dwordx4 v[156:159], v[170:171], off
	v_lshl_add_u64 v[218:219], s[20:21], 0, v[210:211]
	global_load_dwordx4 v[160:163], v[218:219], off
	global_load_dwordx4 v[144:147], v[248:249], off offset:256
	global_load_dwordx4 v[148:151], v[170:171], off offset:256
	s_mov_b64 s[38:39], 0x2000
	v_lshl_add_u64 v[210:211], v[210:211], 0, s[38:39]
	v_lshl_add_u64 v[212:213], v[212:213], 0, s[72:73]
	v_lshl_add_u64 v[214:215], v[214:215], 0, s[72:73]
	s_cmp_ge_u32 s25, 128
	s_cbranch_scc1 .LatB_40
